# NA: one static s_setprio 1 for waves 4-7 (younger wave of each SIMD) over the neighbourhood-attention phase
# speedup vs baseline: 1.0005x; 1.0005x over previous
; #define LAS __attribute__((address_space(3)))
; __device__ __forceinline__ void na_item(const bf16_t* __restrict__ PMIX, const bf16_t* __restrict__ GP, bf16_t* __restrict__ O, const float* __restrict__ bias, int item, int lane, LAS unsigned char* wl) {
;     const int q = lane & 31, hi = lane >> 5;
;     const bool lat = item < 8192;
;     int b, h, gi = 0, jh = 0, qrow;
;     if (lat) { b = item >> 11; h = (item >> 7) & 15; gi = (item >> 1) & 63; jh = item & 1; qrow = b * 4096 + gi * 64 + jh * 32 + q; }
;     else { const int it = item - 8192; b = it >> 7; h = (it >> 3) & 15; qrow = NLAT + b * 256 + (it & 7) * 32 + q; }
;     const int j = jh * 32 + q;
;     const int c0 = min(max(j - 8, 0), 48), r0 = min(max(gi - 4, 0), 56);
;     const bf16_t* qp = PMIX + (size_t)qrow * NMIXP + O_NAQ + h * 64 + hi * 8;
;     bf16x8 qf[4];
; #pragma unroll
;     for (int ks = 0; ks < 4; ++ks) qf[ks] = *reinterpret_cast<const bf16x8*>(qp + ks * 16);
;     f32x16 oT0 = {}, oT1 = {}; float m = -1e30f, l = 0.f;
;     const int ntiles = lat ? 24 : 8;
;     const float* bh = bias + h * (15 * 31);
;     LAS float* lbias = (LAS float*)(wl + 4608);
; __global__ void __launch_bounds__(512, 2) mk_fwd(Args args) {
;     ...
;             const int nna = 8192 + (need_ctx ? 512 : 0);
;             for (int it = gw; it < nna; it += NGW) na_item(PMIX, GP, OB, rel_bias + (size_t)layer * 16 * 15 * 31, it, lane, lds + wid * 5632);
.Lna_norot:
	v_writelane_b32 v255, s34, 38
	s_and_b64 s[2:3], s[34:35], exec
	s_movk_i32 s1, 0x2200
	s_cselect_b32 s79, s1, 0x2000
	v_writelane_b32 v255, s35, 39
	s_cmp_ge_i32 s78, s79
	s_barrier
	s_cbranch_scc1 .LBB0_625
	s_bitcmp1_b32 s0, 2
	s_cbranch_scc0 .Lna_prio_skip
	s_setprio 1
.Lna_prio_skip:
	s_lshl_b32 s80, s89, 3
	s_add_u32 s74, s90, 0x2087a000
	v_readlane_b32 s1, v255, 37
	s_addc_u32 s75, s1, 0
	s_add_u32 s2, s90, 0x2b27a000
	s_addc_u32 s3, s1, 0
	v_readlane_b32 s8, v254, 18
	s_add_u32 s4, s90, 0x572a6000
	v_readlane_b32 s6, v255, 20
	v_readlane_b32 s9, v254, 19
	v_readlane_b32 s10, v254, 20
	v_readlane_b32 s11, v254, 21
	v_readlane_b32 s12, v254, 22
	v_readlane_b32 s13, v254, 23
	v_readlane_b32 s16, v254, 26
	v_readlane_b32 s17, v254, 27
	s_addc_u32 s5, s1, 0
	s_mul_hi_u32 s1, s6, 0x7440
	s_mulk_i32 s6, 0x7440
	v_readlane_b32 s18, v254, 28
	v_readlane_b32 s19, v254, 29
	v_readlane_b32 s20, v254, 30
	v_readlane_b32 s21, v254, 31
	s_mov_b64 s[8:9], s[16:17]
	s_add_u32 s6, s8, s6
	s_mulk_i32 s0, 0x1600
	v_and_b32_e32 v0, 63, v176
	s_addc_u32 s82, s9, s1
	s_add_i32 s88, s0, 0
	v_bfe_u32 v1, v176, 5, 1
	v_lshlrev_b32_e32 v2, 2, v0
	v_mov_b32_e32 v3, s88
	v_bfe_u32 v167, v176, 3, 3
	s_movk_i32 s0, 0x90
	v_lshlrev_b32_e32 v168, 2, v1
	v_and_b32_e32 v128, 28, v2
	v_mad_u32_u24 v5, v167, s0, v3
	v_xor_b32_e32 v169, 0x80, v2
	v_or_b32_e32 v133, 8, v168
	v_lshlrev_b32_e32 v2, 4, v1
	v_mov_b32_e32 v3, v195
	v_or_b32_e32 v132, 32, v168
	v_lshl_add_u64 v[142:143], s[74:75], 0, v[2:3]
	v_lshlrev_b32_e32 v2, 1, v133
	v_and_b32_e32 v164, 31, v176
	v_lshl_add_u32 v166, v0, 4, s88
	v_or_b32_e32 v0, 3, v128
	v_and_b32_e32 v4, 1, v176
	v_or_b32_e32 v136, 40, v168
	v_lshl_add_u64 v[148:149], s[2:3], 0, v[2:3]
	v_lshl_add_u64 v[150:151], s[4:5], 0, v[2:3]
	v_lshlrev_b32_e32 v2, 1, v132
	v_lshlrev_b32_e32 v194, 3, v1
	v_min_u32_e32 v130, 30, v0
	v_lshlrev_b32_e32 v0, 5, v4
	v_lshlrev_b32_e32 v4, 6, v4
	v_lshl_add_u32 v6, v164, 1, s88
	v_mul_u32_u24_e32 v7, 0x240, v1
	v_mul_u32_u24_e32 v8, 0x90, v133
	v_lshl_add_u64 v[152:153], s[2:3], 0, v[2:3]
	v_lshl_add_u64 v[154:155], s[4:5], 0, v[2:3]
	v_lshlrev_b32_e32 v2, 1, v136
	v_readlane_b32 s7, v255, 21
	v_writelane_b32 v255, s6, 40
	v_bfe_u32 v165, v176, 3, 3
	v_or_b32_e32 v170, 16, v168
	v_or_b32_e32 v171, 17, v168
	v_or_b32_e32 v172, 18, v168
	v_or_b32_e32 v173, 19, v168
	v_or_b32_e32 v174, 24, v168
	v_or_b32_e32 v175, 25, v168
	v_or_b32_e32 v176, 26, v168
	v_or_b32_e32 v177, 27, v168
	v_or_b32_e32 v135, 33, v168
	v_or_b32_e32 v137, 35, v168
	v_or_b32_e32 v134, 34, v168
	v_or_b32_e32 v139, 41, v168
	v_or_b32_e32 v141, 43, v168
	v_or_b32_e32 v138, 42, v168
	v_mov_b32_e32 v129, v195
	v_mov_b32_e32 v131, v195
	v_lshl_add_u64 v[144:145], s[2:3], 0, v[194:195]
	v_lshl_add_u64 v[146:147], s[4:5], 0, v[194:195]
	v_lshl_add_u64 v[156:157], s[2:3], 0, v[2:3]
	v_lshl_add_u64 v[158:159], s[4:5], 0, v[2:3]
	v_or_b32_e32 v178, 0x48, v168
	v_add_u32_e32 v179, 0x47, v168
	v_or_b32_e32 v180, 0x42, v168
	v_or_b32_e32 v181, 0x41, v168
	v_or_b32_e32 v182, 64, v168
	v_add_u32_e32 v183, 63, v168
	v_lshlrev_b32_e32 v160, 1, v194
	v_and_b32_e32 v194, 7, v164
	v_lshlrev_b32_e32 v194, 4, v194
	v_add_u32_e32 v184, v5, v194
	s_mov_b64 s[98:99], 0x14000
	v_mul_u32_u24_e32 v185, 0x90, v164
	v_lshl_add_u32 v185, v1, 4, v185
	v_add_u32_e32 v185, s88, v185
	v_add_u32_e32 v186, v6, v8
	v_bfe_u32 v229, v164, 2, 2
	v_mul_u32_u24_e32 v229, 0x90, v229
	v_bfe_u32 v253, v164, 4, 1
	v_lshl_add_u32 v229, v253, 5, v229
	v_and_b32_e32 v253, 3, v164
	v_lshl_add_u32 v229, v253, 3, v229
	v_add_u32_e32 v229, v229, v7
	v_add_u32_e32 v229, s88, v229
	v_readlane_b32 s14, v254, 24
	v_readlane_b32 s15, v254, 25
	v_readlane_b32 s22, v254, 32
	v_readlane_b32 s23, v254, 33
	s_mov_b64 s[10:11], s[18:19]
	s_mov_b64 s[12:13], s[20:21]
	s_branch .LBB0_596

; __global__ void __launch_bounds__(512, 2) mk_fwd(Args args) {
;     ...
;             for (int it = gw; it < nna; it += NGW) na_item(PMIX, GP, OB, rel_bias + (size_t)layer * 16 * 15 * 31, it, lane, lds + wid * 5632);
;             for (int it = bid; it < (NB * NCHUNK * 2 * 256) / 512; it += G) lru_pass1_item(LA, LU, AGG, it);
.LBB0_625:
	s_setprio 0
	v_readlane_b32 s68, v255, 33
	s_cmpk_eq_i32 s89, 0x100
	s_cbranch_scc0 .Lp1_norot
	s_addk_i32 s91, 0x80
	s_and_b32 s91, s91, 0xff
